# NA band tiles: skip v_sub/v_exp for key blocks a wave's window can never touch (exact zeros), wave-uniform branches
# speedup vs baseline: 1.0015x; 1.0015x over previous
.LBB0_1059:
	v_readfirstlane_b32 s58, v166
	s_bfe_u32 s58, s58, 0x20006
	s_cmp_ge_u32 s58, 2
	s_cbranch_scc1 .Lnx0_s0
	v_sub_f32_e32 v0, v124, v2
	v_exp_f32_e32 v140, v0
	v_sub_f32_e32 v0, v125, v2
	v_exp_f32_e32 v141, v0
	v_sub_f32_e32 v0, v126, v2
	v_exp_f32_e32 v142, v0
	v_sub_f32_e32 v0, v127, v2
	v_exp_f32_e32 v143, v0
	s_branch .Lnx0_j0
.Lnx0_s0:
	v_mov_b32_e32 v140, 0
	v_mov_b32_e32 v141, 0
	v_mov_b32_e32 v142, 0
	v_mov_b32_e32 v143, 0
.Lnx0_j0:
	s_cmp_eq_u32 s58, 3
	s_cbranch_scc1 .Lnx0_s1
	v_sub_f32_e32 v0, v128, v2
	v_exp_f32_e32 v144, v0
	v_sub_f32_e32 v0, v129, v2
	v_exp_f32_e32 v145, v0
	v_sub_f32_e32 v0, v130, v2
	v_exp_f32_e32 v146, v0
	v_sub_f32_e32 v0, v131, v2
	v_exp_f32_e32 v147, v0
	s_branch .Lnx0_j1
.Lnx0_s1:
	v_mov_b32_e32 v144, 0
	v_mov_b32_e32 v145, 0
	v_mov_b32_e32 v146, 0
	v_mov_b32_e32 v147, 0
.Lnx0_j1:
	s_cmp_eq_u32 s58, 0
	s_cbranch_scc1 .Lnx0_s2
	v_sub_f32_e32 v0, v132, v2
	v_exp_f32_e32 v148, v0
	v_sub_f32_e32 v0, v133, v2
	v_exp_f32_e32 v149, v0
	v_sub_f32_e32 v0, v134, v2
	v_exp_f32_e32 v150, v0
	v_sub_f32_e32 v0, v135, v2
	v_exp_f32_e32 v151, v0
	s_branch .Lnx0_j2
.Lnx0_s2:
	v_mov_b32_e32 v148, 0
	v_mov_b32_e32 v149, 0
	v_mov_b32_e32 v150, 0
	v_mov_b32_e32 v151, 0
.Lnx0_j2:
	s_cmp_le_u32 s58, 1
	s_cbranch_scc1 .Lnx0_s3
	v_sub_f32_e32 v0, v136, v2
	v_exp_f32_e32 v152, v0
	v_sub_f32_e32 v0, v137, v2
	v_exp_f32_e32 v153, v0
	v_sub_f32_e32 v0, v138, v2
	v_exp_f32_e32 v154, v0
	s_branch .Lnx0_j3
.Lnx0_s3:
	v_mov_b32_e32 v152, 0
	v_mov_b32_e32 v153, 0
	v_mov_b32_e32 v154, 0
.Lnx0_j3:
	v_sub_f32_e32 v0, v139, v2
	s_mov_b64 s[58:59], 0

.LBB0_1098:
	v_readfirstlane_b32 s0, v166
	s_bfe_u32 s0, s0, 0x20006
	s_cmp_ge_u32 s0, 2
	s_cbranch_scc1 .Lnx1_s0
	v_sub_f32_e32 v0, v132, v165
	v_exp_f32_e32 v108, v0
	v_sub_f32_e32 v0, v133, v165
	v_exp_f32_e32 v109, v0
	v_sub_f32_e32 v0, v134, v165
	v_exp_f32_e32 v110, v0
	v_sub_f32_e32 v0, v135, v165
	v_exp_f32_e32 v111, v0
	s_branch .Lnx1_j0
.Lnx1_s0:
	v_mov_b32_e32 v108, 0
	v_mov_b32_e32 v109, 0
	v_mov_b32_e32 v110, 0
	v_mov_b32_e32 v111, 0
.Lnx1_j0:
	s_cmp_eq_u32 s0, 3
	s_cbranch_scc1 .Lnx1_s1
	v_sub_f32_e32 v0, v136, v165
	v_exp_f32_e32 v116, v0
	v_sub_f32_e32 v0, v137, v165
	v_exp_f32_e32 v117, v0
	v_sub_f32_e32 v0, v138, v165
	v_exp_f32_e32 v118, v0
	v_sub_f32_e32 v0, v139, v165
	v_exp_f32_e32 v119, v0
	s_branch .Lnx1_j1
.Lnx1_s1:
	v_mov_b32_e32 v116, 0
	v_mov_b32_e32 v117, 0
	v_mov_b32_e32 v118, 0
	v_mov_b32_e32 v119, 0
.Lnx1_j1:
	s_cmp_eq_u32 s0, 0
	s_cbranch_scc1 .Lnx1_s2
	v_sub_f32_e32 v0, v140, v165
	v_exp_f32_e32 v112, v0
	v_sub_f32_e32 v0, v141, v165
	v_exp_f32_e32 v113, v0
	v_sub_f32_e32 v0, v142, v165
	v_exp_f32_e32 v114, v0
	v_sub_f32_e32 v0, v143, v165
	v_exp_f32_e32 v115, v0
	s_branch .Lnx1_j2
.Lnx1_s2:
	v_mov_b32_e32 v112, 0
	v_mov_b32_e32 v113, 0
	v_mov_b32_e32 v114, 0
	v_mov_b32_e32 v115, 0
.Lnx1_j2:
	s_cmp_le_u32 s0, 1
	s_cbranch_scc1 .Lnx1_s3
	v_sub_f32_e32 v0, v144, v165
	v_exp_f32_e32 v120, v0
	v_sub_f32_e32 v0, v145, v165
	v_exp_f32_e32 v121, v0
	v_sub_f32_e32 v0, v146, v165
	v_exp_f32_e32 v122, v0
	s_branch .Lnx1_j3
.Lnx1_s3:
	v_mov_b32_e32 v120, 0
	v_mov_b32_e32 v121, 0
	v_mov_b32_e32 v122, 0
.Lnx1_j3:
	v_sub_f32_e32 v0, v147, v165
	s_mov_b64 s[0:1], 0

.LBB0_1145:
	v_readfirstlane_b32 s0, v166
	s_bfe_u32 s0, s0, 0x20006
	s_cmp_ge_u32 s0, 2
	s_cbranch_scc1 .Lnx2_s0
	v_sub_f32_e32 v0, v124, v2
	v_exp_f32_e32 v140, v0
	v_sub_f32_e32 v0, v125, v2
	v_exp_f32_e32 v141, v0
	v_sub_f32_e32 v0, v126, v2
	v_exp_f32_e32 v142, v0
	v_sub_f32_e32 v0, v127, v2
	v_exp_f32_e32 v143, v0
	s_branch .Lnx2_j0

.Lnx2_j0:
	s_cmp_eq_u32 s0, 3
	s_cbranch_scc1 .Lnx2_s1
	v_sub_f32_e32 v0, v128, v2
	v_exp_f32_e32 v144, v0
	v_sub_f32_e32 v0, v129, v2
	v_exp_f32_e32 v145, v0
	v_sub_f32_e32 v0, v130, v2
	v_exp_f32_e32 v146, v0
	v_sub_f32_e32 v0, v131, v2
	v_exp_f32_e32 v147, v0
	s_branch .Lnx2_j1

.Lnx2_j1:
	s_cmp_eq_u32 s0, 0
	s_cbranch_scc1 .Lnx2_s2
	v_sub_f32_e32 v0, v132, v2
	v_exp_f32_e32 v148, v0
	v_sub_f32_e32 v0, v133, v2
	v_exp_f32_e32 v149, v0
	v_sub_f32_e32 v0, v134, v2
	v_exp_f32_e32 v150, v0
	v_sub_f32_e32 v0, v135, v2
	v_exp_f32_e32 v151, v0
	s_branch .Lnx2_j2

.Lnx2_j2:
	s_cmp_le_u32 s0, 1
	s_cbranch_scc1 .Lnx2_s3
	v_sub_f32_e32 v0, v136, v2
	v_exp_f32_e32 v152, v0
	v_sub_f32_e32 v0, v137, v2
	v_exp_f32_e32 v153, v0
	v_sub_f32_e32 v0, v138, v2
	v_exp_f32_e32 v154, v0
	s_branch .Lnx2_j3

.Lnx2_j3:
	v_sub_f32_e32 v0, v139, v2
	s_mov_b64 s[0:1], 0
